# early L2 writeback: wave 0 of each WG issues buffer_wbl2 when it arrives at a grid barrier
# baseline (speedup 1.0000x reference)
; __device__ __forceinline__ void xcd_barrier_complete(unsigned* bar, unsigned x, unsigned& nloc, unsigned& nx) {
;     const unsigned G = gridDim.x * gridDim.y * gridDim.z;
;     unsigned sum, cnt, mine, sp = 0u;
;     for (;;) {
;         sum = 0u; cnt = 0u; mine = 0u;
; __device__ __forceinline__ void xcd_barrier(const XcdBarrier& b) {
;     asm volatile("s_waitcnt vmcnt(0)" ::: "memory");
;     __syncthreads();
;     if (threadIdx.x == 0) {
;         unsigned* bar = b.bar;
;         __builtin_amdgcn_s_waitcnt(0);
;         unsigned nloc = b.st[0], nx = b.st[1];
;         if (nloc == 0u) { xcd_barrier_complete(bar, b.x, nloc, nx); b.st[0] = nloc; b.st[1] = nx; }
.LBB0_66:
	s_or_b64 exec, exec, s[8:9]
	v_readfirstlane_b32 s98, v0
	s_nop 3
	s_cmp_lt_u32 s98, 64
	s_cbranch_scc0 .Lewb_0
	buffer_wbl2 sc1
.Lewb_0:
	s_waitcnt vmcnt(0)
	s_barrier
	s_mov_b64 s[0:1], exec
	v_readlane_b32 s4, v244, 12
	v_readlane_b32 s5, v244, 13
	s_and_b64 s[4:5], s[0:1], s[4:5]
	s_mov_b64 exec, s[4:5]
	s_cbranch_execz .LBB0_118
	s_add_i32 s3, 0, 0x20000
	v_mov_b32_e32 v2, s3
	s_waitcnt vmcnt(0) expcnt(0) lgkmcnt(0)
	ds_read_b32 v4, v2
	s_add_i32 s3, 0, 0x20004
	v_mov_b32_e32 v2, s3
	ds_read_b32 v2, v2
	s_waitcnt lgkmcnt(1)
	v_cmp_ne_u32_e32 vcc, 0, v4
	s_cbranch_vccnz .LBB0_82
	v_readlane_b32 s6, v244, 31
	v_readlane_b32 s7, v244, 32
	s_load_dwordx2 s[4:5], s[6:7], 0x4
	s_mov_b32 s3, 1
	v_mov_b32_e32 v18, 0
	s_waitcnt lgkmcnt(0)
	s_mul_i32 s10, s4, s33
	s_mul_i32 s10, s10, s5
	s_branch .LBB0_70

; __device__ __forceinline__ void xcd_barrier(const XcdBarrier& b) {
;     asm volatile("s_waitcnt vmcnt(0)" ::: "memory");
;     __syncthreads();
.LBB0_448:
	v_readfirstlane_b32 s98, v0
	s_nop 3
	s_cmp_lt_u32 s98, 64
	s_cbranch_scc0 .Lewb_1
	buffer_wbl2 sc1

; __device__ __forceinline__ void xcd_barrier(const XcdBarrier& b) {
;     asm volatile("s_waitcnt vmcnt(0)" ::: "memory");
;     __syncthreads();
;     if (threadIdx.x == 0) {
;         unsigned* bar = b.bar;
;         __builtin_amdgcn_s_waitcnt(0);
;         unsigned nloc = b.st[0], nx = b.st[1];
;         if (nloc == 0u) { xcd_barrier_complete(bar, b.x, nloc, nx); b.st[0] = nloc; b.st[1] = nx; }
.LBB0_578:
	s_or_b64 exec, exec, s[20:21]
	v_readfirstlane_b32 s98, v0
	s_nop 3
	s_cmp_lt_u32 s98, 64
	s_cbranch_scc0 .Lewb_2
	buffer_wbl2 sc1
.Lewb_2:
	s_waitcnt vmcnt(0)
	s_barrier
	s_mov_b64 s[0:1], exec
	v_readlane_b32 s4, v244, 12
	v_readlane_b32 s5, v244, 13
	s_and_b64 s[4:5], s[0:1], s[4:5]
	s_mov_b64 exec, s[4:5]
	s_cbranch_execz .LBB0_630
	s_add_i32 s4, 0, 0x20000
	v_mov_b32_e32 v2, s4
	s_waitcnt vmcnt(0) expcnt(0) lgkmcnt(0)
	ds_read_b32 v4, v2
	s_add_i32 s4, 0, 0x20004
	v_mov_b32_e32 v2, s4
	ds_read_b32 v2, v2
	s_waitcnt lgkmcnt(1)
	v_cmp_ne_u32_e32 vcc, 0, v4
	s_cbranch_vccnz .LBB0_594
	v_readlane_b32 s6, v244, 31
	v_readlane_b32 s7, v244, 32
	s_load_dwordx2 s[4:5], s[6:7], 0x4
	s_mov_b32 s10, 1
	v_mov_b32_e32 v18, 0
	s_waitcnt lgkmcnt(0)
	s_mul_i32 s11, s4, s33
	s_mul_i32 s11, s11, s5
	s_branch .LBB0_582

; __device__ __forceinline__ void xcd_barrier(const XcdBarrier& b) {
;     asm volatile("s_waitcnt vmcnt(0)" ::: "memory");
;     __syncthreads();
.LBB0_747:
	s_or_b64 exec, exec, s[0:1]
	v_readfirstlane_b32 s98, v0
	s_nop 3
	s_cmp_lt_u32 s98, 64
	s_cbranch_scc0 .Lewb_4
	buffer_wbl2 sc1

; __device__ __forceinline__ void xcd_barrier(const XcdBarrier& b) {
;     asm volatile("s_waitcnt vmcnt(0)" ::: "memory");
;     __syncthreads();
;     if (threadIdx.x == 0) {
;         unsigned* bar = b.bar;
;         __builtin_amdgcn_s_waitcnt(0);
;         unsigned nloc = b.st[0], nx = b.st[1];
;         if (nloc == 0u) { xcd_barrier_complete(bar, b.x, nloc, nx); b.st[0] = nloc; b.st[1] = nx; }
.Lewb_6:
	s_waitcnt vmcnt(0)
	s_barrier
	s_mov_b64 s[6:7], exec
	v_readlane_b32 s8, v244, 12
	v_readlane_b32 s9, v244, 13
	s_and_b64 s[8:9], s[6:7], s[8:9]
	s_mov_b64 exec, s[8:9]
	s_cbranch_execz .LBB0_951
	s_add_i32 s3, 0, 0x20000
	s_waitcnt vmcnt(7)
	v_mov_b32_e32 v2, s3
	s_waitcnt vmcnt(0) expcnt(0) lgkmcnt(0)
	ds_read_b32 v4, v2
	s_add_i32 s3, 0, 0x20004
	v_mov_b32_e32 v2, s3
	ds_read_b32 v2, v2
	s_waitcnt lgkmcnt(1)
	v_cmp_ne_u32_e32 vcc, 0, v4
	s_cbranch_vccnz .LBB0_915
	v_readlane_b32 s10, v244, 31
	v_readlane_b32 s11, v244, 32
	s_load_dwordx2 s[8:9], s[10:11], 0x4
	s_mov_b32 s3, 1
	v_mov_b32_e32 v18, 0
	s_waitcnt lgkmcnt(0)
	s_mul_i32 s14, s8, s33
	s_mul_i32 s14, s14, s9
	s_branch .LBB0_903

; __device__ __forceinline__ void xcd_barrier(const XcdBarrier& b) {
;     asm volatile("s_waitcnt vmcnt(0)" ::: "memory");
;     __syncthreads();
;     if (threadIdx.x == 0) {
;         unsigned* bar = b.bar;
;         __builtin_amdgcn_s_waitcnt(0);
;         unsigned nloc = b.st[0], nx = b.st[1];
;         if (nloc == 0u) { xcd_barrier_complete(bar, b.x, nloc, nx); b.st[0] = nloc; b.st[1] = nx; }
.LBB0_1164:
	s_or_b64 exec, exec, s[6:7]
	v_readfirstlane_b32 s98, v0
	s_nop 3
	s_cmp_lt_u32 s98, 64
	s_cbranch_scc0 .Lewb_8
	buffer_wbl2 sc1
.Lewb_8:
	s_waitcnt vmcnt(0)
	s_barrier
	s_mov_b64 s[2:3], exec
	v_readlane_b32 s6, v244, 12
	v_readlane_b32 s7, v244, 13
	s_and_b64 s[6:7], s[2:3], s[6:7]
	s_mov_b64 exec, s[6:7]
	s_cbranch_execz .LBB0_1216
	s_add_i32 s6, 0, 0x20000
	v_mov_b32_e32 v1, s6
	s_waitcnt vmcnt(0) expcnt(0) lgkmcnt(0)
	ds_read_b32 v3, v1
	s_add_i32 s6, 0, 0x20004
	v_mov_b32_e32 v1, s6
	ds_read_b32 v1, v1
	s_waitcnt lgkmcnt(1)
	v_cmp_ne_u32_e32 vcc, 0, v3
	s_cbranch_vccnz .LBB0_1180
	v_readlane_b32 s8, v244, 31
	v_readlane_b32 s9, v244, 32
	s_load_dwordx2 s[6:7], s[8:9], 0x4
	s_mov_b32 s12, 1
	v_mov_b32_e32 v17, 0
	s_waitcnt lgkmcnt(0)
	s_mul_i32 s13, s6, s33
	s_mul_i32 s13, s13, s7
	s_branch .LBB0_1168
